# MLA attention epilogue: in-register 4x4 DPP transpose + dwordx2 stores instead of the 64-step ds_bpermute chain (on top of the seam edits)
# baseline (speedup 1.0000x reference)
.LBB0_1450:
	s_and_saveexec_b64 s[0:1], s[6:7]
	ds_write_b32 v191, v199
	s_or_b64 exec, exec, s[0:1]
	s_waitcnt lgkmcnt(0)
	ds_read_b128 v[82:85], v188
	ds_read_b128 v[86:89], v188 offset:32
	ds_read_b128 v[90:93], v188 offset:64
	ds_read_b128 v[94:97], v188 offset:96
	s_lshl_b32 s0, s89, 11
	s_add_u32 s0, s26, s0
	s_addc_u32 s1, s4, 0
	s_lshl_b32 s3, s97, 1
	s_add_u32 s3, s0, s3
	s_addc_u32 s5, s1, 0
	s_ashr_i32 s97, s96, 31
	s_lshl_b64 s[0:1], s[96:97], 11
	s_add_u32 s0, s3, s0
	s_addc_u32 s1, s5, s1
	s_mov_b32 s10, 0x33333333
	s_mov_b32 s11, 0x33333333
	s_mov_b32 s12, 0xaaaaaaaa
	s_mov_b32 s13, 0xaaaaaaaa
	s_mov_b64 s[8:9], 0x4000
	v_and_b32_e32 v107, 3, v184
	v_add_u32_e32 v107, v107, v186
	v_and_b32_e32 v108, 28, v189
	v_lshlrev_b32_e32 v107, 11, v107
	v_lshl_add_u32 v98, v108, 1, v107
	v_mov_b32_e32 v99, 0
	v_mov_b32_e32 v107, 0x5040100
	v_mov_b32_e32 v108, 0x3020706
	v_lshl_add_u64 v[98:99], v[98:99], 0, s[0:1]
	v_cndmask_b32_e64 v106, v107, v108, s[12:13]
	v_lshl_add_u64 v[100:101], v[98:99], 0, s[8:9]
	v_lshl_add_u64 v[102:103], v[100:101], 0, s[8:9]
	v_lshl_add_u64 v[104:105], v[102:103], 0, s[8:9]
	s_waitcnt lgkmcnt(0)
	v_rcp_f32_e32 v82, v82
	v_rcp_f32_e32 v83, v83
	v_rcp_f32_e32 v84, v84
	v_rcp_f32_e32 v85, v85
	v_rcp_f32_e32 v86, v86
	v_rcp_f32_e32 v87, v87
	v_rcp_f32_e32 v88, v88
	v_rcp_f32_e32 v89, v89
	v_rcp_f32_e32 v90, v90
	v_rcp_f32_e32 v91, v91
	v_rcp_f32_e32 v92, v92
	v_rcp_f32_e32 v93, v93
	v_rcp_f32_e32 v94, v94
	v_rcp_f32_e32 v95, v95
	v_rcp_f32_e32 v96, v96
	v_rcp_f32_e32 v97, v97
	s_nop 0
	v_mul_f32_e32 v18, v18, v82
	v_mul_f32_e32 v19, v19, v83
	v_mul_f32_e32 v20, v20, v84
	v_mul_f32_e32 v21, v21, v85
	v_mul_f32_e32 v22, v22, v86
	v_mul_f32_e32 v23, v23, v87
	v_mul_f32_e32 v24, v24, v88
	v_mul_f32_e32 v25, v25, v89
	v_mul_f32_e32 v26, v26, v90
	v_mul_f32_e32 v27, v27, v91
	v_mul_f32_e32 v28, v28, v92
	v_mul_f32_e32 v29, v29, v93
	v_mul_f32_e32 v30, v30, v94
	v_mul_f32_e32 v31, v31, v95
	v_mul_f32_e32 v32, v32, v96
	v_mul_f32_e32 v33, v33, v97
	v_cvt_pk_bf16_f32 v18, v18, v19
	v_cvt_pk_bf16_f32 v20, v20, v21
	v_cvt_pk_bf16_f32 v22, v22, v23
	v_cvt_pk_bf16_f32 v24, v24, v25
	v_cvt_pk_bf16_f32 v26, v26, v27
	v_cvt_pk_bf16_f32 v28, v28, v29
	v_cvt_pk_bf16_f32 v30, v30, v31
	v_cvt_pk_bf16_f32 v32, v32, v33
	s_nop 1
	v_mov_b32_dpp v19, v18 quad_perm:[1,0,3,2] row_mask:0xf bank_mask:0xf
	v_mov_b32_dpp v21, v20 quad_perm:[1,0,3,2] row_mask:0xf bank_mask:0xf
	v_mov_b32_dpp v23, v22 quad_perm:[1,0,3,2] row_mask:0xf bank_mask:0xf
	v_mov_b32_dpp v25, v24 quad_perm:[1,0,3,2] row_mask:0xf bank_mask:0xf
	v_mov_b32_dpp v27, v26 quad_perm:[1,0,3,2] row_mask:0xf bank_mask:0xf
	v_mov_b32_dpp v29, v28 quad_perm:[1,0,3,2] row_mask:0xf bank_mask:0xf
	v_mov_b32_dpp v31, v30 quad_perm:[1,0,3,2] row_mask:0xf bank_mask:0xf
	v_mov_b32_dpp v33, v32 quad_perm:[1,0,3,2] row_mask:0xf bank_mask:0xf
	v_perm_b32 v18, v19, v18, v106
	v_perm_b32 v20, v21, v20, v106
	v_perm_b32 v22, v23, v22, v106
	v_perm_b32 v24, v25, v24, v106
	v_perm_b32 v26, v27, v26, v106
	v_perm_b32 v28, v29, v28, v106
	v_perm_b32 v30, v31, v30, v106
	v_perm_b32 v32, v33, v32, v106
	v_cndmask_b32_e64 v19, v18, v20, s[10:11]
	v_cndmask_b32_e64 v23, v22, v24, s[10:11]
	v_cndmask_b32_e64 v27, v26, v28, s[10:11]
	v_cndmask_b32_e64 v31, v30, v32, s[10:11]
	s_nop 1
	v_mov_b32_dpp v21, v19 quad_perm:[2,3,0,1] row_mask:0xf bank_mask:0xf
	v_mov_b32_dpp v25, v23 quad_perm:[2,3,0,1] row_mask:0xf bank_mask:0xf
	v_mov_b32_dpp v29, v27 quad_perm:[2,3,0,1] row_mask:0xf bank_mask:0xf
	v_mov_b32_dpp v33, v31 quad_perm:[2,3,0,1] row_mask:0xf bank_mask:0xf
	v_cndmask_b32_e64 v19, v20, v21, s[10:11]
	v_cndmask_b32_e64 v18, v21, v18, s[10:11]
	v_cndmask_b32_e64 v23, v24, v25, s[10:11]
	v_cndmask_b32_e64 v22, v25, v22, s[10:11]
	v_cndmask_b32_e64 v27, v28, v29, s[10:11]
	v_cndmask_b32_e64 v26, v29, v26, s[10:11]
	v_cndmask_b32_e64 v31, v32, v33, s[10:11]
	v_cndmask_b32_e64 v30, v33, v30, s[10:11]
	global_store_dwordx2 v[98:99], v[18:19], off
	global_store_dwordx2 v[100:101], v[22:23], off
	global_store_dwordx2 v[102:103], v[26:27], off
	global_store_dwordx2 v[104:105], v[30:31], off
	v_mul_f32_e32 v34, v34, v82
	v_mul_f32_e32 v35, v35, v83
	v_mul_f32_e32 v36, v36, v84
	v_mul_f32_e32 v37, v37, v85
	v_mul_f32_e32 v38, v38, v86
	v_mul_f32_e32 v39, v39, v87
	v_mul_f32_e32 v40, v40, v88
	v_mul_f32_e32 v41, v41, v89
	v_mul_f32_e32 v42, v42, v90
	v_mul_f32_e32 v43, v43, v91
	v_mul_f32_e32 v44, v44, v92
	v_mul_f32_e32 v45, v45, v93
	v_mul_f32_e32 v46, v46, v94
	v_mul_f32_e32 v47, v47, v95
	v_mul_f32_e32 v48, v48, v96
	v_mul_f32_e32 v49, v49, v97
	v_cvt_pk_bf16_f32 v34, v34, v35
	v_cvt_pk_bf16_f32 v36, v36, v37
	v_cvt_pk_bf16_f32 v38, v38, v39
	v_cvt_pk_bf16_f32 v40, v40, v41
	v_cvt_pk_bf16_f32 v42, v42, v43
	v_cvt_pk_bf16_f32 v44, v44, v45
	v_cvt_pk_bf16_f32 v46, v46, v47
	v_cvt_pk_bf16_f32 v48, v48, v49
	s_nop 1
	v_mov_b32_dpp v35, v34 quad_perm:[1,0,3,2] row_mask:0xf bank_mask:0xf
	v_mov_b32_dpp v37, v36 quad_perm:[1,0,3,2] row_mask:0xf bank_mask:0xf
	v_mov_b32_dpp v39, v38 quad_perm:[1,0,3,2] row_mask:0xf bank_mask:0xf
	v_mov_b32_dpp v41, v40 quad_perm:[1,0,3,2] row_mask:0xf bank_mask:0xf
	v_mov_b32_dpp v43, v42 quad_perm:[1,0,3,2] row_mask:0xf bank_mask:0xf
	v_mov_b32_dpp v45, v44 quad_perm:[1,0,3,2] row_mask:0xf bank_mask:0xf
	v_mov_b32_dpp v47, v46 quad_perm:[1,0,3,2] row_mask:0xf bank_mask:0xf
	v_mov_b32_dpp v49, v48 quad_perm:[1,0,3,2] row_mask:0xf bank_mask:0xf
	v_perm_b32 v34, v35, v34, v106
	v_perm_b32 v36, v37, v36, v106
	v_perm_b32 v38, v39, v38, v106
	v_perm_b32 v40, v41, v40, v106
	v_perm_b32 v42, v43, v42, v106
	v_perm_b32 v44, v45, v44, v106
	v_perm_b32 v46, v47, v46, v106
	v_perm_b32 v48, v49, v48, v106
	v_cndmask_b32_e64 v35, v34, v36, s[10:11]
	v_cndmask_b32_e64 v39, v38, v40, s[10:11]
	v_cndmask_b32_e64 v43, v42, v44, s[10:11]
	v_cndmask_b32_e64 v47, v46, v48, s[10:11]
	s_nop 1
	v_mov_b32_dpp v37, v35 quad_perm:[2,3,0,1] row_mask:0xf bank_mask:0xf
	v_mov_b32_dpp v41, v39 quad_perm:[2,3,0,1] row_mask:0xf bank_mask:0xf
	v_mov_b32_dpp v45, v43 quad_perm:[2,3,0,1] row_mask:0xf bank_mask:0xf
	v_mov_b32_dpp v49, v47 quad_perm:[2,3,0,1] row_mask:0xf bank_mask:0xf
	v_cndmask_b32_e64 v35, v36, v37, s[10:11]
	v_cndmask_b32_e64 v34, v37, v34, s[10:11]
	v_cndmask_b32_e64 v39, v40, v41, s[10:11]
	v_cndmask_b32_e64 v38, v41, v38, s[10:11]
	v_cndmask_b32_e64 v43, v44, v45, s[10:11]
	v_cndmask_b32_e64 v42, v45, v42, s[10:11]
	v_cndmask_b32_e64 v47, v48, v49, s[10:11]
	v_cndmask_b32_e64 v46, v49, v46, s[10:11]
	global_store_dwordx2 v[98:99], v[34:35], off offset:64
	global_store_dwordx2 v[100:101], v[38:39], off offset:64
	global_store_dwordx2 v[102:103], v[42:43], off offset:64
	global_store_dwordx2 v[104:105], v[46:47], off offset:64
	v_mul_f32_e32 v50, v50, v82
	v_mul_f32_e32 v51, v51, v83
	v_mul_f32_e32 v52, v52, v84
	v_mul_f32_e32 v53, v53, v85
	v_mul_f32_e32 v54, v54, v86
	v_mul_f32_e32 v55, v55, v87
	v_mul_f32_e32 v56, v56, v88
	v_mul_f32_e32 v57, v57, v89
	v_mul_f32_e32 v58, v58, v90
	v_mul_f32_e32 v59, v59, v91
	v_mul_f32_e32 v60, v60, v92
	v_mul_f32_e32 v61, v61, v93
	v_mul_f32_e32 v62, v62, v94
	v_mul_f32_e32 v63, v63, v95
	v_mul_f32_e32 v64, v64, v96
	v_mul_f32_e32 v65, v65, v97
	v_cvt_pk_bf16_f32 v50, v50, v51
	v_cvt_pk_bf16_f32 v52, v52, v53
	v_cvt_pk_bf16_f32 v54, v54, v55
	v_cvt_pk_bf16_f32 v56, v56, v57
	v_cvt_pk_bf16_f32 v58, v58, v59
	v_cvt_pk_bf16_f32 v60, v60, v61
	v_cvt_pk_bf16_f32 v62, v62, v63
	v_cvt_pk_bf16_f32 v64, v64, v65
	s_nop 1
	v_mov_b32_dpp v51, v50 quad_perm:[1,0,3,2] row_mask:0xf bank_mask:0xf
	v_mov_b32_dpp v53, v52 quad_perm:[1,0,3,2] row_mask:0xf bank_mask:0xf
	v_mov_b32_dpp v55, v54 quad_perm:[1,0,3,2] row_mask:0xf bank_mask:0xf
	v_mov_b32_dpp v57, v56 quad_perm:[1,0,3,2] row_mask:0xf bank_mask:0xf
	v_mov_b32_dpp v59, v58 quad_perm:[1,0,3,2] row_mask:0xf bank_mask:0xf
	v_mov_b32_dpp v61, v60 quad_perm:[1,0,3,2] row_mask:0xf bank_mask:0xf
	v_mov_b32_dpp v63, v62 quad_perm:[1,0,3,2] row_mask:0xf bank_mask:0xf
	v_mov_b32_dpp v65, v64 quad_perm:[1,0,3,2] row_mask:0xf bank_mask:0xf
	v_perm_b32 v50, v51, v50, v106
	v_perm_b32 v52, v53, v52, v106
	v_perm_b32 v54, v55, v54, v106
	v_perm_b32 v56, v57, v56, v106
	v_perm_b32 v58, v59, v58, v106
	v_perm_b32 v60, v61, v60, v106
	v_perm_b32 v62, v63, v62, v106
	v_perm_b32 v64, v65, v64, v106
	v_cndmask_b32_e64 v51, v50, v52, s[10:11]
	v_cndmask_b32_e64 v55, v54, v56, s[10:11]
	v_cndmask_b32_e64 v59, v58, v60, s[10:11]
	v_cndmask_b32_e64 v63, v62, v64, s[10:11]
	s_nop 1
	v_mov_b32_dpp v53, v51 quad_perm:[2,3,0,1] row_mask:0xf bank_mask:0xf
	v_mov_b32_dpp v57, v55 quad_perm:[2,3,0,1] row_mask:0xf bank_mask:0xf
	v_mov_b32_dpp v61, v59 quad_perm:[2,3,0,1] row_mask:0xf bank_mask:0xf
	v_mov_b32_dpp v65, v63 quad_perm:[2,3,0,1] row_mask:0xf bank_mask:0xf
	v_cndmask_b32_e64 v51, v52, v53, s[10:11]
	v_cndmask_b32_e64 v50, v53, v50, s[10:11]
	v_cndmask_b32_e64 v55, v56, v57, s[10:11]
	v_cndmask_b32_e64 v54, v57, v54, s[10:11]
	v_cndmask_b32_e64 v59, v60, v61, s[10:11]
	v_cndmask_b32_e64 v58, v61, v58, s[10:11]
	v_cndmask_b32_e64 v63, v64, v65, s[10:11]
	v_cndmask_b32_e64 v62, v65, v62, s[10:11]
	global_store_dwordx2 v[98:99], v[50:51], off offset:128
	global_store_dwordx2 v[100:101], v[54:55], off offset:128
	global_store_dwordx2 v[102:103], v[58:59], off offset:128
	global_store_dwordx2 v[104:105], v[62:63], off offset:128
	v_mul_f32_e32 v66, v66, v82
	v_mul_f32_e32 v67, v67, v83
	v_mul_f32_e32 v68, v68, v84
	v_mul_f32_e32 v69, v69, v85
	v_mul_f32_e32 v70, v70, v86
	v_mul_f32_e32 v71, v71, v87
	v_mul_f32_e32 v72, v72, v88
	v_mul_f32_e32 v73, v73, v89
	v_mul_f32_e32 v74, v74, v90
	v_mul_f32_e32 v75, v75, v91
	v_mul_f32_e32 v76, v76, v92
	v_mul_f32_e32 v77, v77, v93
	v_mul_f32_e32 v78, v78, v94
	v_mul_f32_e32 v79, v79, v95
	v_mul_f32_e32 v80, v80, v96
	v_mul_f32_e32 v81, v81, v97
	v_cvt_pk_bf16_f32 v66, v66, v67
	v_cvt_pk_bf16_f32 v68, v68, v69
	v_cvt_pk_bf16_f32 v70, v70, v71
	v_cvt_pk_bf16_f32 v72, v72, v73
	v_cvt_pk_bf16_f32 v74, v74, v75
	v_cvt_pk_bf16_f32 v76, v76, v77
	v_cvt_pk_bf16_f32 v78, v78, v79
	v_cvt_pk_bf16_f32 v80, v80, v81
	s_nop 1
	v_mov_b32_dpp v67, v66 quad_perm:[1,0,3,2] row_mask:0xf bank_mask:0xf
	v_mov_b32_dpp v69, v68 quad_perm:[1,0,3,2] row_mask:0xf bank_mask:0xf
	v_mov_b32_dpp v71, v70 quad_perm:[1,0,3,2] row_mask:0xf bank_mask:0xf
	v_mov_b32_dpp v73, v72 quad_perm:[1,0,3,2] row_mask:0xf bank_mask:0xf
	v_mov_b32_dpp v75, v74 quad_perm:[1,0,3,2] row_mask:0xf bank_mask:0xf
	v_mov_b32_dpp v77, v76 quad_perm:[1,0,3,2] row_mask:0xf bank_mask:0xf
	v_mov_b32_dpp v79, v78 quad_perm:[1,0,3,2] row_mask:0xf bank_mask:0xf
	v_mov_b32_dpp v81, v80 quad_perm:[1,0,3,2] row_mask:0xf bank_mask:0xf
	v_perm_b32 v66, v67, v66, v106
	v_perm_b32 v68, v69, v68, v106
	v_perm_b32 v70, v71, v70, v106
	v_perm_b32 v72, v73, v72, v106
	v_perm_b32 v74, v75, v74, v106
	v_perm_b32 v76, v77, v76, v106
	v_perm_b32 v78, v79, v78, v106
	v_perm_b32 v80, v81, v80, v106
	v_cndmask_b32_e64 v67, v66, v68, s[10:11]
	v_cndmask_b32_e64 v71, v70, v72, s[10:11]
	v_cndmask_b32_e64 v75, v74, v76, s[10:11]
	v_cndmask_b32_e64 v79, v78, v80, s[10:11]
	s_nop 1
	v_mov_b32_dpp v69, v67 quad_perm:[2,3,0,1] row_mask:0xf bank_mask:0xf
	v_mov_b32_dpp v73, v71 quad_perm:[2,3,0,1] row_mask:0xf bank_mask:0xf
	v_mov_b32_dpp v77, v75 quad_perm:[2,3,0,1] row_mask:0xf bank_mask:0xf
	v_mov_b32_dpp v81, v79 quad_perm:[2,3,0,1] row_mask:0xf bank_mask:0xf
	v_cndmask_b32_e64 v67, v68, v69, s[10:11]
	v_cndmask_b32_e64 v66, v69, v66, s[10:11]
	v_cndmask_b32_e64 v71, v72, v73, s[10:11]
	v_cndmask_b32_e64 v70, v73, v70, s[10:11]
	v_cndmask_b32_e64 v75, v76, v77, s[10:11]
	v_cndmask_b32_e64 v74, v77, v74, s[10:11]
	v_cndmask_b32_e64 v79, v80, v81, s[10:11]
	v_cndmask_b32_e64 v78, v81, v78, s[10:11]
	global_store_dwordx2 v[98:99], v[66:67], off offset:192
	global_store_dwordx2 v[100:101], v[70:71], off offset:192
	global_store_dwordx2 v[102:103], v[74:75], off offset:192
	global_store_dwordx2 v[104:105], v[78:79], off offset:192
	s_branch .LBB0_1421
